# in_o non-swap (Yt) K-loop pipelined with 3-quad LDS ring; in_e tile prologue issues A/W loads before consuming the row-scale load
# speedup vs baseline: 1.0350x; 1.0055x over previous
; DI int otid() { int t = threadIdx.x; asm volatile("" : "+v"(t)); return t; }
; #define A256_LOADH(kt_, hf_) { a0 = la.ld1(kt_, (hf_) * 4 + 0, tid); a1 = la.ld1(kt_, (hf_) * 4 + 1, tid); a2 = la.ld1(kt_, (hf_) * 4 + 2, tid); a3 = la.ld1(kt_, (hf_) * 4 + 3, tid); }
; template <bool swap, class LA>
; DI void gemm256_ws(const LA& la, const bf16_t* Wt, const int KS, const int nk, bf16_t* smem, f32x16 (&acc)[8]) {
;   const int tid = otid();
;   const int lane = tid & 63, w = tid >> 6, wm = w >> 1, wn = w & 1, l32 = lane & 31, h = lane >> 5;
;   const int fb = swap ? wm : wn, tbk = swap ? wn : wm;
;   const bf16_t* wp0 = Wt + ((size_t)(fb * 2) * KS) * 512 + lane * 8;
;   const bf16_t* wp1 = wp0 + (size_t)KS * 512;
;   uint4 a0, a1, a2, a3;
;   bf16x8 w00, w01, w02, w03, w10, w11, w12, w13;
;   const int last = nk - 1;
;     ...
;   A256_LOADH(0, 0) A256_STH(smem, 0)
;   A256_LOADH(0, 1) A256_STH(smem, 1)
;   W256_LD(0, 0, w00, w10) W256_LD(0, 1, w01, w11) W256_LD(0, 2, w02, w12) W256_LD(0, 3, w03, w13)
;   __syncthreads();
;   const int aoff = (tbk * 128 + l32) * LDT + h * 8;
.LBB0_194:
	s_and_b64 vcc, exec, s[18:19]
	s_cbranch_vccz .LBB0_185
	v_mov_b32_e32 v0, v234
	s_add_u32 s18, s10, 0x40000
	v_lshlrev_b32_e32 v2, 3, v0
	v_ashrrev_i32_e32 v3, 31, v2
	v_lshlrev_b64 v[196:197], 1, v[2:3]
	v_add_u32_e32 v6, 0x800, v2
	v_add_u32_e32 v8, 0x1000, v2
	v_add_u32_e32 v2, 0x1800, v2
	v_lshlrev_b32_e32 v42, 11, v0
	v_ashrrev_i32_e32 v3, 31, v2
	v_lshlrev_b32_e32 v44, 4, v0
	v_lshrrev_b32_e32 v45, 3, v0
	v_and_b32_e32 v47, 0xfffff9f, v0
	v_lshrrev_b32_e32 v46, 1, v0
	v_and_b32_e32 v50, 63, v0
	v_and_b32_e32 v0, 0x20000, v42
	v_ashrrev_i32_e32 v7, 31, v6
	v_ashrrev_i32_e32 v9, 31, v8
	v_lshlrev_b64 v[202:203], 1, v[2:3]
	v_mov_b32_e32 v43, v1
	v_and_b32_e32 v42, 0x3f0, v44
	v_and_b32_e32 v44, 0x70, v44
	v_lshl_add_u64 v[48:49], s[8:9], 0, v[0:1]
	v_lshl_add_u64 v[4:5], s[10:11], 0, v[196:197]
	v_lshlrev_b64 v[198:199], 1, v[6:7]
	v_lshlrev_b64 v[200:201], 1, v[8:9]
	v_lshl_add_u64 v[2:3], s[10:11], 0, v[202:203]
	s_addc_u32 s19, s11, 0
	v_mad_u64_u32 v[204:205], s[8:9], v45, s0, v[44:45]
	v_lshl_add_u64 v[44:45], v[0:1], 0, s[16:17]
	v_lshlrev_b32_e32 v0, 4, v50
	v_lshl_add_u64 v[42:43], v[48:49], 0, v[42:43]
	v_lshl_add_u64 v[6:7], s[10:11], 0, v[198:199]
	v_lshl_add_u64 v[8:9], s[10:11], 0, v[200:201]
	global_load_dwordx4 v[10:13], v[4:5], off
	global_load_dwordx4 v[14:17], v[6:7], off
	global_load_dwordx4 v[18:21], v[8:9], off
	global_load_dwordx4 v[22:25], v[2:3], off
	v_lshl_add_u64 v[2:3], s[18:19], 0, v[196:197]
	v_lshl_add_u64 v[208:209], v[44:45], 0, v[0:1]
	v_add_co_u32_e32 v44, vcc, s94, v42
	global_load_dwordx4 v[26:29], v[2:3], off
	v_lshl_add_u64 v[2:3], s[18:19], 0, v[198:199]
	v_addc_co_u32_e32 v45, vcc, 0, v43, vcc
	v_lshl_add_u64 v[4:5], s[18:19], 0, v[200:201]
	v_lshl_add_u64 v[6:7], s[18:19], 0, v[202:203]
	global_load_dwordx4 v[30:33], v[2:3], off
	global_load_dwordx4 v[34:37], v[4:5], off
	global_load_dwordx4 v[38:41], v[6:7], off
	global_load_dwordx4 v[154:157], v[42:43], off
	global_load_dwordx4 v[158:161], v[44:45], off
	global_load_dwordx4 v[150:153], v[42:43], off offset:1024
	global_load_dwordx4 v[146:149], v[44:45], off offset:1024
	global_load_dwordx4 v[138:141], v[42:43], off offset:2048
	global_load_dwordx4 v[142:145], v[44:45], off offset:2048
	global_load_dwordx4 v[134:137], v[42:43], off offset:3072
	global_load_dwordx4 v[130:133], v[44:45], off offset:3072
	v_mov_b32_e32 v232, v42
	v_mov_b32_e32 v233, v43
	v_mov_b32_e32 v2, 0
	v_and_b32_e32 v46, 16, v46
	v_mov_b32_e32 v219, 0x12000
	s_mov_b32 s13, 0
	v_mov_b32_e32 v3, v2
	v_mov_b32_e32 v4, v2
	v_mov_b32_e32 v5, v2
	v_mov_b32_e32 v6, v2
	v_mov_b32_e32 v7, v2
	v_mov_b32_e32 v8, v2
	v_mov_b32_e32 v9, v2
	v_mad_u64_u32 v[206:207], s[8:9], v47, s0, v[46:47]
	v_lshl_add_u64 v[210:211], s[14:15], 0, v[196:197]
	v_lshl_add_u64 v[212:213], s[14:15], 0, v[202:203]
	v_lshl_add_u64 v[214:215], s[14:15], 0, v[198:199]
	v_lshl_add_u64 v[216:217], s[14:15], 0, v[200:201]
	v_mov_b32_e32 v42, v2
	v_mov_b32_e32 v43, v2
	v_mov_b32_e32 v44, v2
	v_mov_b32_e32 v45, v2
	v_mov_b32_e32 v46, v2
	v_mov_b32_e32 v47, v2
	v_mov_b32_e32 v48, v2
	v_mov_b32_e32 v49, v2
	v_mov_b32_e32 v82, v2
	v_mov_b32_e32 v83, v2
	v_mov_b32_e32 v84, v2
	v_mov_b32_e32 v85, v2
	v_mov_b32_e32 v86, v2
	v_mov_b32_e32 v87, v2
	v_mov_b32_e32 v88, v2
	v_mov_b32_e32 v89, v2
	v_mov_b32_e32 v90, v2
	v_mov_b32_e32 v91, v2
	v_mov_b32_e32 v92, v2
	v_mov_b32_e32 v93, v2
	v_mov_b32_e32 v94, v2
	v_mov_b32_e32 v95, v2
	s_waitcnt vmcnt(15)
	ds_write_b128 v204, v[10:13]
	s_waitcnt vmcnt(11)
	ds_write_b128 v204, v[26:29] offset:18432
	ds_write_b128 v204, v[14:17] offset:4608
	ds_write_b128 v204, v[18:21] offset:9216
	ds_write_b128 v204, v[22:25] offset:13824
	s_waitcnt vmcnt(10)
	ds_write_b128 v204, v[30:33] offset:23040
	s_waitcnt vmcnt(9)
	ds_write_b128 v204, v[34:37] offset:27648
	s_waitcnt vmcnt(8)
	ds_write_b128 v204, v[38:41] offset:32256
	v_mov_b32_e32 v10, v2
	v_mov_b32_e32 v11, v2
	v_mov_b32_e32 v12, v2
	v_mov_b32_e32 v13, v2
	v_mov_b32_e32 v14, v2
	v_mov_b32_e32 v15, v2
	v_mov_b32_e32 v16, v2
	v_mov_b32_e32 v17, v2
	v_mov_b32_e32 v34, v2
	v_mov_b32_e32 v35, v2
	v_mov_b32_e32 v36, v2
	v_mov_b32_e32 v37, v2
	v_mov_b32_e32 v38, v2
	v_mov_b32_e32 v39, v2
	v_mov_b32_e32 v40, v2
	v_mov_b32_e32 v41, v2
	v_mov_b32_e32 v18, v2
	v_mov_b32_e32 v19, v2
	v_mov_b32_e32 v20, v2
	v_mov_b32_e32 v21, v2
	v_mov_b32_e32 v22, v2
	v_mov_b32_e32 v23, v2
	v_mov_b32_e32 v24, v2
	v_mov_b32_e32 v25, v2
	v_mov_b32_e32 v26, v2
	v_mov_b32_e32 v27, v2
	v_mov_b32_e32 v28, v2
	v_mov_b32_e32 v29, v2
	v_mov_b32_e32 v30, v2
	v_mov_b32_e32 v31, v2
	v_mov_b32_e32 v32, v2
	v_mov_b32_e32 v33, v2
	v_mov_b32_e32 v96, v2
	v_mov_b32_e32 v97, v2
	v_mov_b32_e32 v50, v2
	v_mov_b32_e32 v51, v2
	v_mov_b32_e32 v52, v2
	v_mov_b32_e32 v53, v2
	v_mov_b32_e32 v54, v2
	v_mov_b32_e32 v55, v2
	v_mov_b32_e32 v56, v2
	v_mov_b32_e32 v57, v2
	v_mov_b32_e32 v58, v2
	v_mov_b32_e32 v59, v2
	v_mov_b32_e32 v60, v2
	v_mov_b32_e32 v61, v2
	v_mov_b32_e32 v62, v2
	v_mov_b32_e32 v63, v2
	v_mov_b32_e32 v64, v2
	v_mov_b32_e32 v65, v2
	v_mov_b32_e32 v98, v2
	v_mov_b32_e32 v99, v2
	v_mov_b32_e32 v100, v2
	v_mov_b32_e32 v101, v2
	v_mov_b32_e32 v102, v2
	v_mov_b32_e32 v103, v2
	v_mov_b32_e32 v104, v2
	v_mov_b32_e32 v105, v2
	v_mov_b32_e32 v106, v2
	v_mov_b32_e32 v107, v2
	v_mov_b32_e32 v108, v2
	v_mov_b32_e32 v109, v2
	v_mov_b32_e32 v110, v2
	v_mov_b32_e32 v111, v2
	v_mov_b32_e32 v112, v2
	v_mov_b32_e32 v113, v2
	v_mov_b32_e32 v66, v2
	v_mov_b32_e32 v67, v2
	v_mov_b32_e32 v68, v2
	v_mov_b32_e32 v69, v2
	v_mov_b32_e32 v70, v2
	v_mov_b32_e32 v71, v2
	v_mov_b32_e32 v72, v2
	v_mov_b32_e32 v73, v2
	v_mov_b32_e32 v74, v2
	v_mov_b32_e32 v75, v2
	v_mov_b32_e32 v76, v2
	v_mov_b32_e32 v77, v2
	v_mov_b32_e32 v78, v2
	v_mov_b32_e32 v79, v2
	v_mov_b32_e32 v80, v2
	v_mov_b32_e32 v81, v2
	v_mov_b32_e32 v114, v2
	v_mov_b32_e32 v115, v2
	v_mov_b32_e32 v116, v2
	v_mov_b32_e32 v117, v2
	v_mov_b32_e32 v118, v2
	v_mov_b32_e32 v119, v2
	v_mov_b32_e32 v120, v2
	v_mov_b32_e32 v121, v2
	v_mov_b32_e32 v122, v2
	v_mov_b32_e32 v123, v2
	v_mov_b32_e32 v124, v2
	v_mov_b32_e32 v125, v2
	v_mov_b32_e32 v126, v2
	v_mov_b32_e32 v127, v2
	v_mov_b32_e32 v128, v2
	v_mov_b32_e32 v129, v2
	s_waitcnt lgkmcnt(0)
	s_barrier
; #define A256_LOADH(kt_, hf_) { a0 = la.ld1(kt_, (hf_) * 4 + 0, tid); a1 = la.ld1(kt_, (hf_) * 4 + 1, tid); a2 = la.ld1(kt_, (hf_) * 4 + 2, tid); a3 = la.ld1(kt_, (hf_) * 4 + 3, tid); }
; template <bool swap, class LA>
; DI void gemm256_ws(const LA& la, const bf16_t* Wt, const int KS, const int nk, bf16_t* smem, f32x16 (&acc)[8]) {
;     ...
;   for (int kt = 0; kt < nk; kt++) {
;     const int cur = kt & 1; const int kn = (kt + 1 < nk) ? kt + 1 : last;
;     const bf16_t* sp = smem + cur * ATILE_E + aoff;
;     bf16_t* nxt = smem + (cur ^ 1) * ATILE_E;
;     A256_LOADH(kn, 0)
;     MMA256(0, w00, w10) W256_LD(kn, 0, w00, w10)
;     MMA256(1, w01, w11) W256_LD(kn, 1, w01, w11)
;     A256_STH(nxt, 0)
;     A256_LOADH(kn, 1)
;     MMA256(2, w02, w12) W256_LD(kn, 2, w02, w12)
;     MMA256(3, w03, w13) W256_LD(kn, 3, w03, w13)
;     A256_STH(nxt, 1)
;     __syncthreads();
;   }
.LBB0_196:
	s_and_b32 s36, s13, 1
	s_mul_i32 s37, s36, 0x9000
	v_add_u32_e32 v0, s37, v206
	ds_read_b128 v[220:223], v0
	ds_read_b128 v[224:227], v0 offset:4608
	ds_read_b128 v[228:231], v0 offset:9216
	s_add_i32 s13, s13, 1
	s_min_u32 s38, s13, 15
	s_xor_b32 s36, s36, 1
	s_mul_i32 s37, s36, 0x9000
	v_add_u32_e32 v195, s37, v204
	s_lshl_b32 s39, s38, 14
	s_lshl_b32 s90, s38, 12
	s_add_u32 s8, s90, 0x10000
	s_mov_b32 s9, 0
	s_add_u32 s36, s10, s39
	s_addc_u32 s37, s11, 0
	v_lshl_add_u64 v[208:209], s[36:37], 0, v[196:197]
	v_lshl_add_u64 v[212:213], s[36:37], 0, v[198:199]
	v_lshl_add_u64 v[244:245], s[36:37], 0, v[200:201]
	v_lshl_add_u64 v[248:249], s[36:37], 0, v[202:203]
	global_load_dwordx4 v[208:211], v[208:209], off
	global_load_dwordx4 v[212:215], v[212:213], off
	global_load_dwordx4 v[244:247], v[244:245], off
	global_load_dwordx4 v[248:251], v[248:249], off
	s_waitcnt vmcnt(10) lgkmcnt(2)
	v_mfma_f32_32x32x16_bf16 v[114:129], v[220:223], v[154:157], v[114:129]
	v_mfma_f32_32x32x16_bf16 v[66:81], v[220:223], v[158:161], v[66:81]
	ds_read_b128 v[220:223], v0 offset:13824
	s_waitcnt lgkmcnt(2)
	v_mfma_f32_32x32x16_bf16 v[98:113], v[224:227], v[154:157], v[98:113]
	v_mfma_f32_32x32x16_bf16 v[50:65], v[224:227], v[158:161], v[50:65]
	ds_read_b128 v[224:227], v0 offset:32
	s_waitcnt lgkmcnt(2)
	v_mfma_f32_32x32x16_bf16 v[82:97], v[228:231], v[154:157], v[82:97]
	v_mfma_f32_32x32x16_bf16 v[18:33], v[228:231], v[158:161], v[18:33]
	ds_read_b128 v[228:231], v0 offset:4640
	s_waitcnt lgkmcnt(2)
	v_mfma_f32_32x32x16_bf16 v[34:49], v[220:223], v[154:157], v[34:49]
	v_mfma_f32_32x32x16_bf16 v[2:17], v[220:223], v[158:161], v[2:17]
	ds_read_b128 v[220:223], v0 offset:9248
	v_lshl_add_u64 v[154:155], v[232:233], 0, s[90:91]
	global_load_dwordx4 v[154:157], v[154:155], off
	v_lshl_add_u64 v[158:159], v[232:233], 0, s[8:9]
	global_load_dwordx4 v[158:161], v[158:159], off
	s_waitcnt vmcnt(10) lgkmcnt(2)
	v_mfma_f32_32x32x16_bf16 v[114:129], v[224:227], v[150:153], v[114:129]
	v_mfma_f32_32x32x16_bf16 v[66:81], v[224:227], v[146:149], v[66:81]
	ds_read_b128 v[224:227], v0 offset:13856
	s_waitcnt lgkmcnt(2)
	v_mfma_f32_32x32x16_bf16 v[98:113], v[228:231], v[150:153], v[98:113]
	v_mfma_f32_32x32x16_bf16 v[50:65], v[228:231], v[146:149], v[50:65]
	ds_read_b128 v[228:231], v0 offset:64
	s_waitcnt lgkmcnt(2)
	v_mfma_f32_32x32x16_bf16 v[82:97], v[220:223], v[150:153], v[82:97]
	v_mfma_f32_32x32x16_bf16 v[18:33], v[220:223], v[146:149], v[18:33]
	ds_read_b128 v[220:223], v0 offset:4672
	s_waitcnt lgkmcnt(2)
	v_mfma_f32_32x32x16_bf16 v[34:49], v[224:227], v[150:153], v[34:49]
	v_mfma_f32_32x32x16_bf16 v[2:17], v[224:227], v[146:149], v[2:17]
	ds_read_b128 v[224:227], v0 offset:9280
	v_lshl_add_u64 v[150:151], v[232:233], 0, s[90:91]
	global_load_dwordx4 v[150:153], v[150:151], off offset:1024
	v_lshl_add_u64 v[146:147], v[232:233], 0, s[8:9]
	global_load_dwordx4 v[146:149], v[146:147], off offset:1024
	s_waitcnt vmcnt(4)
	ds_write_b128 v195, v[208:211]
	ds_write_b128 v195, v[212:215] offset:4608
	ds_write_b128 v195, v[244:247] offset:9216
	ds_write_b128 v195, v[248:251] offset:13824
	s_add_u32 s36, s18, s39
	s_addc_u32 s37, s19, 0
	v_lshl_add_u64 v[208:209], s[36:37], 0, v[196:197]
	v_lshl_add_u64 v[212:213], s[36:37], 0, v[198:199]
	v_lshl_add_u64 v[244:245], s[36:37], 0, v[200:201]
	v_lshl_add_u64 v[248:249], s[36:37], 0, v[202:203]
	global_load_dwordx4 v[208:211], v[208:209], off
	global_load_dwordx4 v[212:215], v[212:213], off
	global_load_dwordx4 v[244:247], v[244:245], off
	global_load_dwordx4 v[248:251], v[248:249], off
	s_waitcnt lgkmcnt(6)
	v_mfma_f32_32x32x16_bf16 v[114:129], v[228:231], v[138:141], v[114:129]
	v_mfma_f32_32x32x16_bf16 v[66:81], v[228:231], v[142:145], v[66:81]
	ds_read_b128 v[228:231], v0 offset:13888
	s_waitcnt lgkmcnt(6)
	v_mfma_f32_32x32x16_bf16 v[98:113], v[220:223], v[138:141], v[98:113]
	v_mfma_f32_32x32x16_bf16 v[50:65], v[220:223], v[142:145], v[50:65]
	ds_read_b128 v[220:223], v0 offset:96
	s_waitcnt lgkmcnt(6)
	v_mfma_f32_32x32x16_bf16 v[82:97], v[224:227], v[138:141], v[82:97]
	v_mfma_f32_32x32x16_bf16 v[18:33], v[224:227], v[142:145], v[18:33]
	ds_read_b128 v[224:227], v0 offset:4704
	s_waitcnt lgkmcnt(2)
	v_mfma_f32_32x32x16_bf16 v[34:49], v[228:231], v[138:141], v[34:49]
	v_mfma_f32_32x32x16_bf16 v[2:17], v[228:231], v[142:145], v[2:17]
	ds_read_b128 v[228:231], v0 offset:9312
	v_lshl_add_u64 v[138:139], v[232:233], 0, s[90:91]
	global_load_dwordx4 v[138:141], v[138:139], off offset:2048
	v_lshl_add_u64 v[142:143], v[232:233], 0, s[8:9]
	global_load_dwordx4 v[142:145], v[142:143], off offset:2048
	s_waitcnt lgkmcnt(2)
	v_mfma_f32_32x32x16_bf16 v[114:129], v[220:223], v[134:137], v[114:129]
	v_mfma_f32_32x32x16_bf16 v[66:81], v[220:223], v[130:133], v[66:81]
	ds_read_b128 v[220:223], v0 offset:13920
	s_waitcnt lgkmcnt(2)
	v_mfma_f32_32x32x16_bf16 v[98:113], v[224:227], v[134:137], v[98:113]
	v_mfma_f32_32x32x16_bf16 v[50:65], v[224:227], v[130:133], v[50:65]
	s_waitcnt lgkmcnt(1)
	v_mfma_f32_32x32x16_bf16 v[82:97], v[228:231], v[134:137], v[82:97]
	v_mfma_f32_32x32x16_bf16 v[18:33], v[228:231], v[130:133], v[18:33]
	s_waitcnt lgkmcnt(0)
	v_mfma_f32_32x32x16_bf16 v[34:49], v[220:223], v[134:137], v[34:49]
	v_mfma_f32_32x32x16_bf16 v[2:17], v[220:223], v[130:133], v[2:17]
	v_lshl_add_u64 v[134:135], v[232:233], 0, s[90:91]
	global_load_dwordx4 v[134:137], v[134:135], off offset:3072
	v_lshl_add_u64 v[130:131], v[232:233], 0, s[8:9]
	global_load_dwordx4 v[130:133], v[130:131], off offset:3072
	s_waitcnt vmcnt(4)
	ds_write_b128 v195, v[208:211] offset:18432
	ds_write_b128 v195, v[212:215] offset:23040
	ds_write_b128 v195, v[244:247] offset:27648
	ds_write_b128 v195, v[248:251] offset:32256
	s_cmp_lg_u32 s13, 15
	s_waitcnt lgkmcnt(0)
	s_barrier
; #define A256_LOADH(kt_, hf_) { a0 = la.ld1(kt_, (hf_) * 4 + 0, tid); a1 = la.ld1(kt_, (hf_) * 4 + 1, tid); a2 = la.ld1(kt_, (hf_) * 4 + 2, tid); a3 = la.ld1(kt_, (hf_) * 4 + 3, tid); }
; template <bool swap, class LA>
; DI void gemm256_ws(const LA& la, const bf16_t* Wt, const int KS, const int nk, bf16_t* smem, f32x16 (&acc)[8]) {
;     ...
;   for (int kt = 0; kt < nk; kt++) {
;     const int cur = kt & 1; const int kn = (kt + 1 < nk) ? kt + 1 : last;
;     const bf16_t* sp = smem + cur * ATILE_E + aoff;
;     bf16_t* nxt = smem + (cur ^ 1) * ATILE_E;
;     A256_LOADH(kn, 0)
;     MMA256(0, w00, w10) W256_LD(kn, 0, w00, w10)
;     MMA256(1, w01, w11) W256_LD(kn, 1, w01, w11)
;     A256_STH(nxt, 0)
;     A256_LOADH(kn, 1)
;     MMA256(2, w02, w12) W256_LD(kn, 2, w02, w12)
;     MMA256(3, w03, w13) W256_LD(kn, 3, w03, w13)
;     A256_STH(nxt, 1)
;     __syncthreads();
;   }
	s_cbranch_scc1 .LBB0_196
	s_waitcnt vmcnt(0)
	ds_read_b128 v[208:211], v206 offset:36864
	s_add_u32 s8, s10, 0x3c000
	s_addc_u32 s9, s11, 0
	v_lshl_add_u64 v[212:213], s[8:9], 0, v[202:203]
	v_xor_b32_e32 v240, 2, v238
	v_xor_b32_e32 v241, 1, v238
	v_mov_b32_e32 v244, v219
	s_waitcnt vmcnt(6) lgkmcnt(0)
	v_mfma_f32_32x32x16_bf16 v[114:129], v[208:211], v[154:157], v[114:129]
	v_mfma_f32_32x32x16_bf16 v[66:81], v[208:211], v[158:161], v[66:81]
	ds_read_b128 v[208:211], v206 offset:41472
	s_waitcnt lgkmcnt(0)
	v_mfma_f32_32x32x16_bf16 v[98:113], v[208:211], v[154:157], v[98:113]
	v_mfma_f32_32x32x16_bf16 v[50:65], v[208:211], v[158:161], v[50:65]
	ds_read_b128 v[208:211], v206 offset:46080
	s_waitcnt lgkmcnt(0)
	v_mfma_f32_32x32x16_bf16 v[82:97], v[208:211], v[154:157], v[82:97]
	v_mfma_f32_32x32x16_bf16 v[18:33], v[208:211], v[158:161], v[18:33]
	ds_read_b128 v[208:211], v206 offset:50688
	s_waitcnt lgkmcnt(0)
	v_mfma_f32_32x32x16_bf16 v[34:49], v[208:211], v[154:157], v[34:49]
	ds_read_b128 v[154:157], v206 offset:36896
	s_waitcnt vmcnt(5) lgkmcnt(0)
	v_mfma_f32_32x32x16_bf16 v[114:129], v[154:157], v[150:153], v[114:129]
	s_waitcnt vmcnt(4)
	v_mfma_f32_32x32x16_bf16 v[66:81], v[154:157], v[146:149], v[66:81]
	ds_read_b128 v[154:157], v206 offset:41504
	s_waitcnt lgkmcnt(0)
	v_mfma_f32_32x32x16_bf16 v[98:113], v[154:157], v[150:153], v[98:113]
	v_mfma_f32_32x32x16_bf16 v[50:65], v[154:157], v[146:149], v[50:65]
	ds_read_b128 v[154:157], v206 offset:46112
	s_waitcnt lgkmcnt(0)
	v_mfma_f32_32x32x16_bf16 v[82:97], v[154:157], v[150:153], v[82:97]
	v_mfma_f32_32x32x16_bf16 v[18:33], v[154:157], v[146:149], v[18:33]
	ds_read_b128 v[154:157], v206 offset:50720
	v_mfma_f32_32x32x16_bf16 v[2:17], v[208:211], v[158:161], v[2:17]
	v_lshl_add_u64 v[158:159], s[8:9], 0, v[196:197]
	v_lshl_add_u64 v[160:161], s[8:9], 0, v[198:199]
	v_lshl_add_u64 v[208:209], s[8:9], 0, v[200:201]
	s_add_u32 s8, s10, 0x7c000
	s_addc_u32 s9, s11, 0
	s_waitcnt lgkmcnt(0)
	v_mfma_f32_32x32x16_bf16 v[34:49], v[154:157], v[150:153], v[34:49]
	global_load_dwordx4 v[150:153], v[158:159], off
	s_nop 0
	global_load_dwordx4 v[158:161], v[160:161], off
	s_nop 0
	global_load_dwordx4 v[208:211], v[208:209], off
	s_nop 0
	global_load_dwordx4 v[212:215], v[212:213], off
	s_waitcnt vmcnt(3)
	ds_write_b128 v204, v[150:153]
	s_waitcnt vmcnt(2)
	ds_write_b128 v204, v[158:161] offset:4608
	s_waitcnt vmcnt(1)
	ds_write_b128 v204, v[208:211] offset:9216
	s_waitcnt vmcnt(0)
	ds_write_b128 v204, v[212:215] offset:13824
	v_mfma_f32_32x32x16_bf16 v[2:17], v[154:157], v[146:149], v[2:17]
	ds_read_b128 v[146:149], v206 offset:36928
	v_lshl_add_u64 v[150:151], s[8:9], 0, v[200:201]
	v_lshl_add_u64 v[154:155], s[8:9], 0, v[202:203]
	s_waitcnt lgkmcnt(0)
	v_mfma_f32_32x32x16_bf16 v[114:129], v[146:149], v[138:141], v[114:129]
	v_mfma_f32_32x32x16_bf16 v[66:81], v[146:149], v[142:145], v[66:81]
	ds_read_b128 v[146:149], v206 offset:41536
	s_waitcnt lgkmcnt(0)
	v_mfma_f32_32x32x16_bf16 v[98:113], v[146:149], v[138:141], v[98:113]
	v_mfma_f32_32x32x16_bf16 v[50:65], v[146:149], v[142:145], v[50:65]
	ds_read_b128 v[146:149], v206 offset:46144
	s_waitcnt lgkmcnt(0)
	v_mfma_f32_32x32x16_bf16 v[82:97], v[146:149], v[138:141], v[82:97]
	v_mfma_f32_32x32x16_bf16 v[18:33], v[146:149], v[142:145], v[18:33]
	ds_read_b128 v[146:149], v206 offset:50752
	s_waitcnt lgkmcnt(0)
	v_mfma_f32_32x32x16_bf16 v[34:49], v[146:149], v[138:141], v[34:49]
	ds_read_b128 v[138:141], v206 offset:36960
	s_waitcnt lgkmcnt(0)
	v_mfma_f32_32x32x16_bf16 v[114:129], v[138:141], v[134:137], v[114:129]
	v_mfma_f32_32x32x16_bf16 v[66:81], v[138:141], v[130:133], v[66:81]
	ds_read_b128 v[138:141], v206 offset:41568
	v_mfma_f32_32x32x16_bf16 v[2:17], v[146:149], v[142:145], v[2:17]
	v_lshl_add_u64 v[142:143], s[8:9], 0, v[196:197]
	v_lshl_add_u64 v[146:147], s[8:9], 0, v[198:199]
	s_waitcnt lgkmcnt(0)
	v_mfma_f32_32x32x16_bf16 v[98:113], v[138:141], v[134:137], v[98:113]
	v_mfma_f32_32x32x16_bf16 v[50:65], v[138:141], v[130:133], v[50:65]
	ds_read_b128 v[138:141], v206 offset:46176
	global_load_dwordx4 v[142:145], v[142:143], off
	s_nop 0
	global_load_dwordx4 v[146:149], v[146:147], off
	s_nop 0
	global_load_dwordx4 v[150:153], v[150:151], off
	s_nop 0
	global_load_dwordx4 v[154:157], v[154:155], off
	s_waitcnt lgkmcnt(0)
	v_mfma_f32_32x32x16_bf16 v[82:97], v[138:141], v[134:137], v[82:97]
	v_mfma_f32_32x32x16_bf16 v[18:33], v[138:141], v[130:133], v[18:33]
	ds_read_b128 v[138:141], v206 offset:50784
	s_waitcnt vmcnt(3)
	ds_write_b128 v204, v[142:145] offset:18432
	s_waitcnt vmcnt(2)
	ds_write_b128 v204, v[146:149] offset:23040
	s_waitcnt vmcnt(1)
	ds_write_b128 v204, v[150:153] offset:27648
	s_waitcnt vmcnt(0)
	ds_write_b128 v204, v[154:157] offset:32256
	s_waitcnt lgkmcnt(4)
	v_mfma_f32_32x32x16_bf16 v[34:49], v[138:141], v[134:137], v[34:49]
	s_waitcnt lgkmcnt(0)
	s_barrier
	v_mfma_f32_32x32x16_bf16 v[2:17], v[138:141], v[130:133], v[2:17]
	s_mov_b64 s[8:9], -1
	s_and_b64 vcc, exec, s[2:3]
	s_cbranch_vccnz .LBB0_186

; #define A256_LOADH(kt_, hf_) { a0 = la.ld1(kt_, (hf_) * 4 + 0, tid); a1 = la.ld1(kt_, (hf_) * 4 + 1, tid); a2 = la.ld1(kt_, (hf_) * 4 + 2, tid); a3 = la.ld1(kt_, (hf_) * 4 + 3, tid); }
; #define ZERO_ACC8(a) { _Pragma("unroll") for (int i_ = 0; i_ < 8; i_++) _Pragma("unroll") for (int r_ = 0; r_ < 16; r_++) a[i_][r_] = 0.f; }
; template <bool swap, class LA>
; DI void gemm256_ws(const LA& la, const bf16_t* Wt, const int KS, const int nk, bf16_t* smem, f32x16 (&acc)[8]) {
;     ...
;   A256_LOADH(0, 0) A256_STH(smem, 0)
;   A256_LOADH(0, 1) A256_STH(smem, 1)
;   W256_LD(0, 0, w00, w10) W256_LD(0, 1, w01, w11) W256_LD(0, 2, w02, w12) W256_LD(0, 3, w03, w13)
;   __syncthreads();
; DI void ph_in_e(const Params& P, int g, bf16_t* smem, float* s_rs) {
;     ...
;   for (int it = 0;; it++) {
;     int mt, nt; if (!tile_sched256(bid, it, 28, 7, mt, nt)) break;
;     const int m0 = mt * 256, n0 = nt * 128; const int split = nt >> 2, cin = (nt & 3) * 128;
;     __syncthreads();
;     s_rs[tid] = rs_in[m0 + tid];
;     f32x16 acc[8]; ZERO_ACC8(acc)
;     LoadTile256 la{xb + (size_t)(2 * mt) * 16 * 8192, 16 * 8192};
;     const bool swap = (split != 2);
;     gemm256(la, W + (size_t)n0 * 1024, 64, 16, smem, acc, swap);
.LBB0_479:
	s_mul_hi_i32 s3, s2, 0x92492493
	s_add_i32 s3, s3, s2
	s_lshr_b32 s8, s3, 31
	s_ashr_i32 s3, s3, 7
	s_add_i32 s3, s3, s8
	s_mul_i32 s8, s3, 0xffffff20
	s_add_i32 s2, s8, s2
	s_mul_hi_i32 s8, s2, 0x92492493
	s_add_i32 s8, s8, s2
	s_lshr_b32 s9, s8, 31
	s_ashr_i32 s8, s8, 2
	s_add_i32 s9, s8, s9
	s_add_i32 s10, s9, s94
	s_lshl_b32 s8, s10, 8
	v_add_u32_e32 v2, s8, v163
	v_ashrrev_i32_e32 v3, 31, v2
	v_lshl_add_u64 v[2:3], v[2:3], 2, s[6:7]
	s_barrier
	global_load_dword v233, v[2:3], off
	s_sub_i32 s3, s3, s9
	s_mul_i32 s3, s3, 7
	s_lshl_b32 s12, s10, 1
	s_add_i32 s3, s3, s2
	s_ashr_i32 s13, s12, 31
	s_ashr_i32 s2, s3, 2
	s_lshl_b32 s10, s3, 7
	s_lshl_b64 s[16:17], s[12:13], 18
	s_add_u32 s14, s38, s16
	s_addc_u32 s15, s39, s17
	s_cmp_lg_u32 s2, 2
	s_cselect_b64 s[12:13], -1, 0
	s_ashr_i32 s11, s10, 31
	s_lshl_b64 s[86:87], s[10:11], 11
	s_add_u32 s92, s26, s86
	s_addc_u32 s93, s27, s87
	s_cmp_eq_u32 s2, 2
	s_mov_b64 s[18:19], -1
	s_cbranch_scc1 .LBB0_487
	v_mov_b32_e32 v0, v234
	v_readlane_b32 s18, v253, 2
	v_lshlrev_b32_e32 v2, 3, v0
	v_ashrrev_i32_e32 v3, 31, v2
	v_ashrrev_i32_e32 v48, 6, v0
	v_lshlrev_b64 v[170:171], 1, v[2:3]
	v_add_u32_e32 v6, 0x800, v2
	v_add_u32_e32 v8, 0x1000, v2
	v_add_u32_e32 v2, 0x1800, v2
	v_lshlrev_b32_e32 v49, 4, v0
	v_and_b32_e32 v48, -2, v48
	v_ashrrev_i32_e32 v3, 31, v2
	v_and_b32_e32 v15, 31, v0
	v_lshrrev_b32_e32 v51, 3, v0
	v_lshlrev_b32_e32 v52, 1, v0
	v_lshrrev_b32_e32 v53, 1, v0
	v_and_b32_e32 v0, 0x3f0, v49
	v_and_b32_e32 v50, 0x70, v49
	v_ashrrev_i32_e32 v49, 31, v48
	v_readlane_b32 s19, v253, 3
	v_ashrrev_i32_e32 v7, 31, v6
	v_ashrrev_i32_e32 v9, 31, v8
	v_lshlrev_b64 v[176:177], 1, v[2:3]
	s_add_u32 s18, s14, 0x40000
	v_lshlrev_b64 v[48:49], 16, v[48:49]
	v_lshl_add_u64 v[4:5], s[14:15], 0, v[170:171]
	v_lshlrev_b64 v[172:173], 1, v[6:7]
	v_lshlrev_b64 v[174:175], 1, v[8:9]
	v_lshl_add_u64 v[2:3], s[14:15], 0, v[176:177]
	s_addc_u32 s19, s15, 0
	v_lshl_add_u64 v[48:49], s[92:93], 0, v[48:49]
	v_lshl_add_u64 v[6:7], s[14:15], 0, v[172:173]
	v_lshl_add_u64 v[8:9], s[14:15], 0, v[174:175]
	global_load_dwordx4 v[16:19], v[4:5], off
	global_load_dwordx4 v[20:23], v[6:7], off
	global_load_dwordx4 v[24:27], v[8:9], off
	global_load_dwordx4 v[28:31], v[2:3], off
	v_lshl_add_u64 v[2:3], s[18:19], 0, v[170:171]
	v_lshl_add_u64 v[180:181], v[48:49], 0, v[0:1]
	global_load_dwordx4 v[32:35], v[2:3], off
	v_lshl_add_u64 v[2:3], s[18:19], 0, v[172:173]
	v_add_co_u32_e32 v48, vcc, s47, v180
	v_lshl_add_u64 v[4:5], s[18:19], 0, v[174:175]
	v_lshl_add_u64 v[6:7], s[18:19], 0, v[176:177]
	global_load_dwordx4 v[36:39], v[2:3], off
	global_load_dwordx4 v[40:43], v[4:5], off
	global_load_dwordx4 v[44:47], v[6:7], off
	v_addc_co_u32_e32 v49, vcc, 0, v181, vcc
	global_load_dwordx4 v[154:157], v[48:49], off
	global_load_dwordx4 v[158:161], v[180:181], off
	global_load_dwordx4 v[146:149], v[48:49], off offset:1024
	global_load_dwordx4 v[150:153], v[180:181], off offset:1024
	global_load_dwordx4 v[142:145], v[48:49], off offset:2048
	global_load_dwordx4 v[138:141], v[180:181], off offset:2048
	global_load_dwordx4 v[130:133], v[48:49], off offset:3072
	global_load_dwordx4 v[134:137], v[180:181], off offset:3072
	s_movk_i32 s9, 0x80
	v_mad_u64_u32 v[178:179], s[44:45], v51, s0, v[50:51]
	v_mov_b32_e32 v2, 0
	v_and_or_b32 v15, v52, s9, v15
	v_and_b32_e32 v52, 16, v53
	s_mov_b64 s[44:45], 0x10000
	s_mov_b32 s3, 0
	v_mov_b32_e32 v3, v2
	v_mov_b32_e32 v4, v2
	v_mov_b32_e32 v5, v2
	v_mov_b32_e32 v6, v2
	v_mov_b32_e32 v7, v2
	v_mov_b32_e32 v8, v2
	v_mov_b32_e32 v9, v2
	v_mov_b32_e32 v10, v2
	v_mov_b32_e32 v11, v2
	v_mov_b32_e32 v12, v2
	v_mov_b32_e32 v13, v2
	v_mov_b32_e32 v14, v2
	v_mad_u32_u24 v169, v15, s0, v52
	v_lshl_add_u64 v[182:183], v[180:181], 0, s[44:45]
	v_mov_b32_e32 v15, v2
	v_mov_b32_e32 v48, v2
	v_mov_b32_e32 v49, v2
	v_mov_b32_e32 v82, v2
	v_mov_b32_e32 v83, v2
	v_mov_b32_e32 v84, v2
	v_mov_b32_e32 v85, v2
	v_mov_b32_e32 v86, v2
	v_mov_b32_e32 v87, v2
	v_mov_b32_e32 v88, v2
	v_mov_b32_e32 v89, v2
	v_mov_b32_e32 v90, v2
	v_mov_b32_e32 v91, v2
	v_mov_b32_e32 v92, v2
	v_mov_b32_e32 v93, v2
	v_mov_b32_e32 v94, v2
	v_mov_b32_e32 v95, v2
	v_mov_b32_e32 v96, v2
	v_mov_b32_e32 v97, v2
	v_mov_b32_e32 v50, v2
	s_waitcnt vmcnt(15)
	ds_write_b32 v192, v233
	ds_write_b128 v178, v[16:19]
	s_waitcnt vmcnt(11)
	ds_write_b128 v178, v[32:35] offset:18432
	ds_write_b128 v178, v[20:23] offset:4608
	ds_write_b128 v178, v[24:27] offset:9216
	ds_write_b128 v178, v[28:31] offset:13824
	s_waitcnt vmcnt(10)
	ds_write_b128 v178, v[36:39] offset:23040
	s_waitcnt vmcnt(9)
	ds_write_b128 v178, v[40:43] offset:27648
	s_waitcnt vmcnt(8)
	ds_write_b128 v178, v[44:47] offset:32256
	v_mov_b32_e32 v16, v2
	v_mov_b32_e32 v17, v2
	v_mov_b32_e32 v34, v2
	v_mov_b32_e32 v35, v2
	v_mov_b32_e32 v36, v2
	v_mov_b32_e32 v37, v2
	v_mov_b32_e32 v38, v2
	v_mov_b32_e32 v39, v2
	v_mov_b32_e32 v40, v2
	v_mov_b32_e32 v41, v2
	v_mov_b32_e32 v42, v2
	v_mov_b32_e32 v43, v2
	v_mov_b32_e32 v44, v2
	v_mov_b32_e32 v45, v2
	v_mov_b32_e32 v46, v2
	v_mov_b32_e32 v47, v2
	v_mov_b32_e32 v18, v2
	v_mov_b32_e32 v19, v2
	v_mov_b32_e32 v20, v2
	v_mov_b32_e32 v21, v2
	v_mov_b32_e32 v22, v2
	v_mov_b32_e32 v23, v2
	v_mov_b32_e32 v24, v2
	v_mov_b32_e32 v25, v2
	v_mov_b32_e32 v26, v2
	v_mov_b32_e32 v27, v2
	v_mov_b32_e32 v28, v2
	v_mov_b32_e32 v29, v2
	v_mov_b32_e32 v30, v2
	v_mov_b32_e32 v31, v2
	v_mov_b32_e32 v32, v2
	v_mov_b32_e32 v33, v2
	v_mov_b32_e32 v51, v2
	v_mov_b32_e32 v52, v2
	v_mov_b32_e32 v53, v2
	v_mov_b32_e32 v54, v2
	v_mov_b32_e32 v55, v2
	v_mov_b32_e32 v56, v2
	v_mov_b32_e32 v57, v2
	v_mov_b32_e32 v58, v2
	v_mov_b32_e32 v59, v2
	v_mov_b32_e32 v60, v2
	v_mov_b32_e32 v61, v2
	v_mov_b32_e32 v62, v2
	v_mov_b32_e32 v63, v2
	v_mov_b32_e32 v64, v2
	v_mov_b32_e32 v65, v2
	v_mov_b32_e32 v98, v2
	v_mov_b32_e32 v99, v2
	v_mov_b32_e32 v100, v2
	v_mov_b32_e32 v101, v2
	v_mov_b32_e32 v102, v2
	v_mov_b32_e32 v103, v2
	v_mov_b32_e32 v104, v2
	v_mov_b32_e32 v105, v2
	v_mov_b32_e32 v106, v2
	v_mov_b32_e32 v107, v2
	v_mov_b32_e32 v108, v2
	v_mov_b32_e32 v109, v2
	v_mov_b32_e32 v110, v2
	v_mov_b32_e32 v111, v2
	v_mov_b32_e32 v112, v2
	v_mov_b32_e32 v113, v2
	v_mov_b32_e32 v66, v2
	v_mov_b32_e32 v67, v2
	v_mov_b32_e32 v68, v2
	v_mov_b32_e32 v69, v2
	v_mov_b32_e32 v70, v2
	v_mov_b32_e32 v71, v2
	v_mov_b32_e32 v72, v2
	v_mov_b32_e32 v73, v2
	v_mov_b32_e32 v74, v2
	v_mov_b32_e32 v75, v2
	v_mov_b32_e32 v76, v2
	v_mov_b32_e32 v77, v2
	v_mov_b32_e32 v78, v2
	v_mov_b32_e32 v79, v2
	v_mov_b32_e32 v80, v2
	v_mov_b32_e32 v81, v2
	v_mov_b32_e32 v114, v2
	v_mov_b32_e32 v115, v2
	v_mov_b32_e32 v116, v2
	v_mov_b32_e32 v117, v2
	v_mov_b32_e32 v118, v2
	v_mov_b32_e32 v119, v2
	v_mov_b32_e32 v120, v2
	v_mov_b32_e32 v121, v2
	v_mov_b32_e32 v122, v2
	v_mov_b32_e32 v123, v2
	v_mov_b32_e32 v124, v2
	v_mov_b32_e32 v125, v2
	v_mov_b32_e32 v126, v2
	v_mov_b32_e32 v127, v2
	v_mov_b32_e32 v128, v2
	v_mov_b32_e32 v129, v2
	s_waitcnt lgkmcnt(0)
	s_barrier

; #define A256_LOADH(kt_, hf_) { a0 = la.ld1(kt_, (hf_) * 4 + 0, tid); a1 = la.ld1(kt_, (hf_) * 4 + 1, tid); a2 = la.ld1(kt_, (hf_) * 4 + 2, tid); a3 = la.ld1(kt_, (hf_) * 4 + 3, tid); }
; #define ZERO_ACC8(a) { _Pragma("unroll") for (int i_ = 0; i_ < 8; i_++) _Pragma("unroll") for (int r_ = 0; r_ < 16; r_++) a[i_][r_] = 0.f; }
; template <bool swap, class LA>
; DI void gemm256_ws(const LA& la, const bf16_t* Wt, const int KS, const int nk, bf16_t* smem, f32x16 (&acc)[8]) {
;     ...
;   A256_LOADH(0, 0) A256_STH(smem, 0)
;   A256_LOADH(0, 1) A256_STH(smem, 1)
;   W256_LD(0, 0, w00, w10) W256_LD(0, 1, w01, w11) W256_LD(0, 2, w02, w12) W256_LD(0, 3, w03, w13)
;   __syncthreads();
; DI void ph_in_e(const Params& P, int g, bf16_t* smem, float* s_rs) {
;     ...
;   for (int it = 0;; it++) {
;     int mt, nt; if (!tile_sched256(bid, it, 28, 7, mt, nt)) break;
;     const int m0 = mt * 256, n0 = nt * 128; const int split = nt >> 2, cin = (nt & 3) * 128;
;     __syncthreads();
;     s_rs[tid] = rs_in[m0 + tid];
;     f32x16 acc[8]; ZERO_ACC8(acc)
;     LoadTile256 la{xb + (size_t)(2 * mt) * 16 * 8192, 16 * 8192};
;     const bool swap = (split != 2);
;     gemm256(la, W + (size_t)n0 * 1024, 64, 16, smem, acc, swap);
.LBB0_487:
	s_and_b64 vcc, exec, s[18:19]
	s_cbranch_vccz .LBB0_483
	v_mov_b32_e32 v0, v234
	s_add_u32 s18, s14, 0x40000
	v_lshlrev_b32_e32 v2, 3, v0
	v_ashrrev_i32_e32 v3, 31, v2
	v_lshlrev_b64 v[170:171], 1, v[2:3]
	v_add_u32_e32 v6, 0x800, v2
	v_add_u32_e32 v8, 0x1000, v2
	v_add_u32_e32 v2, 0x1800, v2
	v_ashrrev_i32_e32 v9, 31, v8
	v_ashrrev_i32_e32 v3, 31, v2
	v_ashrrev_i32_e32 v7, 31, v6
	v_lshlrev_b64 v[174:175], 1, v[8:9]
	v_lshlrev_b64 v[176:177], 1, v[2:3]
	v_lshlrev_b32_e32 v40, 11, v0
	v_lshl_add_u64 v[4:5], s[14:15], 0, v[170:171]
	v_lshlrev_b64 v[172:173], 1, v[6:7]
	v_lshl_add_u64 v[16:17], s[14:15], 0, v[174:175]
	v_lshl_add_u64 v[2:3], s[14:15], 0, v[176:177]
	s_addc_u32 s19, s15, 0
	v_lshlrev_b32_e32 v42, 4, v0
	v_lshrrev_b32_e32 v43, 3, v0
	v_and_b32_e32 v45, 0xfffff9f, v0
	v_lshrrev_b32_e32 v44, 1, v0
	v_and_b32_e32 v48, 63, v0
	v_and_b32_e32 v0, 0x20000, v40
	v_lshl_add_u64 v[6:7], s[14:15], 0, v[172:173]
	global_load_dwordx4 v[8:11], v[4:5], off
	global_load_dwordx4 v[12:15], v[6:7], off
	s_nop 0
	global_load_dwordx4 v[16:19], v[16:17], off
	s_nop 0
	global_load_dwordx4 v[20:23], v[2:3], off
	v_lshl_add_u64 v[2:3], s[18:19], 0, v[170:171]
	v_mov_b32_e32 v41, v1
	v_and_b32_e32 v40, 0x3f0, v42
	v_and_b32_e32 v42, 0x70, v42
	v_lshl_add_u64 v[46:47], s[92:93], 0, v[0:1]
	global_load_dwordx4 v[24:27], v[2:3], off
	v_lshl_add_u64 v[2:3], s[18:19], 0, v[172:173]
	v_lshl_add_u64 v[4:5], s[18:19], 0, v[174:175]
	v_lshl_add_u64 v[6:7], s[18:19], 0, v[176:177]
	v_mad_u64_u32 v[178:179], s[18:19], v43, s0, v[42:43]
	v_lshl_add_u64 v[42:43], v[0:1], 0, s[86:87]
	v_lshlrev_b32_e32 v0, 4, v48
	v_lshl_add_u64 v[40:41], v[46:47], 0, v[40:41]
	v_lshl_add_u64 v[182:183], v[42:43], 0, v[0:1]
	v_add_co_u32_e32 v42, vcc, s47, v40
	global_load_dwordx4 v[28:31], v[2:3], off
	global_load_dwordx4 v[32:35], v[4:5], off
	global_load_dwordx4 v[36:39], v[6:7], off
	v_addc_co_u32_e32 v43, vcc, 0, v41, vcc
	global_load_dwordx4 v[154:157], v[40:41], off
	global_load_dwordx4 v[150:153], v[40:41], off offset:1024
	global_load_dwordx4 v[138:141], v[40:41], off offset:2048
	global_load_dwordx4 v[134:137], v[40:41], off offset:3072
	global_load_dwordx4 v[158:161], v[42:43], off
	global_load_dwordx4 v[146:149], v[42:43], off offset:1024
	global_load_dwordx4 v[142:145], v[42:43], off offset:2048
	global_load_dwordx4 v[130:133], v[42:43], off offset:3072
	s_add_u32 s16, s36, s16
	v_mov_b32_e32 v2, 0
	v_and_b32_e32 v44, 16, v44
	s_addc_u32 s17, 0, s17
	s_mov_b32 s3, 0
	v_mov_b32_e32 v3, v2
	v_mov_b32_e32 v4, v2
	v_mov_b32_e32 v5, v2
	v_mov_b32_e32 v6, v2
	v_mov_b32_e32 v7, v2
	v_mad_u64_u32 v[180:181], s[18:19], v45, s0, v[44:45]
	v_lshl_add_u64 v[184:185], s[16:17], 0, v[170:171]
	v_lshl_add_u64 v[186:187], s[16:17], 0, v[176:177]
	v_lshl_add_u64 v[188:189], s[16:17], 0, v[174:175]
	v_lshl_add_u64 v[190:191], s[16:17], 0, v[172:173]
	v_mov_b32_e32 v40, v2
	v_mov_b32_e32 v41, v2
	v_mov_b32_e32 v42, v2
	v_mov_b32_e32 v43, v2
	v_mov_b32_e32 v44, v2
	v_mov_b32_e32 v45, v2
	v_mov_b32_e32 v46, v2
	v_mov_b32_e32 v47, v2
	v_mov_b32_e32 v48, v2
	v_mov_b32_e32 v49, v2
	v_mov_b32_e32 v82, v2
	v_mov_b32_e32 v83, v2
	v_mov_b32_e32 v84, v2
	v_mov_b32_e32 v85, v2
	v_mov_b32_e32 v86, v2
	v_mov_b32_e32 v87, v2
	v_mov_b32_e32 v88, v2
	v_mov_b32_e32 v89, v2
	v_mov_b32_e32 v90, v2
	v_mov_b32_e32 v91, v2
	v_mov_b32_e32 v92, v2
	v_mov_b32_e32 v93, v2
	v_mov_b32_e32 v94, v2
	s_waitcnt vmcnt(15)
	ds_write_b32 v192, v233
	ds_write_b128 v178, v[8:11]
	s_waitcnt vmcnt(11)
	ds_write_b128 v178, v[24:27] offset:18432
	ds_write_b128 v178, v[12:15] offset:4608
	ds_write_b128 v178, v[16:19] offset:9216
	ds_write_b128 v178, v[20:23] offset:13824
	s_waitcnt vmcnt(10)
	ds_write_b128 v178, v[28:31] offset:23040
	s_waitcnt vmcnt(9)
	ds_write_b128 v178, v[32:35] offset:27648
	s_waitcnt vmcnt(8)
	ds_write_b128 v178, v[36:39] offset:32256
	v_mov_b32_e32 v8, v2
	v_mov_b32_e32 v9, v2
	v_mov_b32_e32 v10, v2
	v_mov_b32_e32 v11, v2
	v_mov_b32_e32 v12, v2
	v_mov_b32_e32 v13, v2
	v_mov_b32_e32 v14, v2
	v_mov_b32_e32 v15, v2
	v_mov_b32_e32 v16, v2
	v_mov_b32_e32 v17, v2
	v_mov_b32_e32 v34, v2
	v_mov_b32_e32 v35, v2
	v_mov_b32_e32 v36, v2
	v_mov_b32_e32 v37, v2
	v_mov_b32_e32 v38, v2
	v_mov_b32_e32 v39, v2
	v_mov_b32_e32 v18, v2
	v_mov_b32_e32 v19, v2
	v_mov_b32_e32 v20, v2
	v_mov_b32_e32 v21, v2
	v_mov_b32_e32 v22, v2
	v_mov_b32_e32 v23, v2
	v_mov_b32_e32 v24, v2
	v_mov_b32_e32 v25, v2
	v_mov_b32_e32 v26, v2
	v_mov_b32_e32 v27, v2
	v_mov_b32_e32 v28, v2
	v_mov_b32_e32 v29, v2
	v_mov_b32_e32 v30, v2
	v_mov_b32_e32 v31, v2
	v_mov_b32_e32 v32, v2
	v_mov_b32_e32 v33, v2
	v_mov_b32_e32 v95, v2
	v_mov_b32_e32 v96, v2
	v_mov_b32_e32 v97, v2
	v_mov_b32_e32 v50, v2
	v_mov_b32_e32 v51, v2
	v_mov_b32_e32 v52, v2
	v_mov_b32_e32 v53, v2
	v_mov_b32_e32 v54, v2
	v_mov_b32_e32 v55, v2
	v_mov_b32_e32 v56, v2
	v_mov_b32_e32 v57, v2
	v_mov_b32_e32 v58, v2
	v_mov_b32_e32 v59, v2
	v_mov_b32_e32 v60, v2
	v_mov_b32_e32 v61, v2
	v_mov_b32_e32 v62, v2
	v_mov_b32_e32 v63, v2
	v_mov_b32_e32 v64, v2
	v_mov_b32_e32 v65, v2
	v_mov_b32_e32 v98, v2
	v_mov_b32_e32 v99, v2
	v_mov_b32_e32 v100, v2
	v_mov_b32_e32 v101, v2
	v_mov_b32_e32 v102, v2
	v_mov_b32_e32 v103, v2
	v_mov_b32_e32 v104, v2
	v_mov_b32_e32 v105, v2
	v_mov_b32_e32 v106, v2
	v_mov_b32_e32 v107, v2
	v_mov_b32_e32 v108, v2
	v_mov_b32_e32 v109, v2
	v_mov_b32_e32 v110, v2
	v_mov_b32_e32 v111, v2
	v_mov_b32_e32 v112, v2
	v_mov_b32_e32 v113, v2
	v_mov_b32_e32 v66, v2
	v_mov_b32_e32 v67, v2
	v_mov_b32_e32 v68, v2
	v_mov_b32_e32 v69, v2
	v_mov_b32_e32 v70, v2
	v_mov_b32_e32 v71, v2
	v_mov_b32_e32 v72, v2
	v_mov_b32_e32 v73, v2
	v_mov_b32_e32 v74, v2
	v_mov_b32_e32 v75, v2
	v_mov_b32_e32 v76, v2
	v_mov_b32_e32 v77, v2
	v_mov_b32_e32 v78, v2
	v_mov_b32_e32 v79, v2
	v_mov_b32_e32 v80, v2
	v_mov_b32_e32 v81, v2
	v_mov_b32_e32 v114, v2
	v_mov_b32_e32 v115, v2
	v_mov_b32_e32 v116, v2
	v_mov_b32_e32 v117, v2
	v_mov_b32_e32 v118, v2
	v_mov_b32_e32 v119, v2
	v_mov_b32_e32 v120, v2
	v_mov_b32_e32 v121, v2
	v_mov_b32_e32 v122, v2
	v_mov_b32_e32 v123, v2
	v_mov_b32_e32 v124, v2
	v_mov_b32_e32 v125, v2
	v_mov_b32_e32 v126, v2
	v_mov_b32_e32 v127, v2
	v_mov_b32_e32 v128, v2
	v_mov_b32_e32 v129, v2
	s_waitcnt lgkmcnt(0)
	s_barrier
